# FFN-down epilogue group 1: last gain/bias quad and second-half residual quad also requested early, no wait behind the first half's stores
# baseline (speedup 1.0000x reference)
; DI float bperm(float v, int srclane) { return __int_as_float(__builtin_amdgcn_ds_bpermute(srclane << 2, __float_as_int(v))); }
; DI u32x4 pack8(const float (&v)[8]) { u32x4 w; w.x = pk2(v[0], v[1]); w.y = pk2(v[2], v[3]); w.z = pk2(v[4], v[5]); w.w = pk2(v[6], v[7]); return w; }
; DI void row_stats(const float* STAT, int row, int fq, int lane, float& mu, float& rstd) {
;     const f32x4 a = *(const f32x4*)(STAT + (size_t)row * 32 + fq * 8), b = *(const f32x4*)(STAT + (size_t)row * 32 + fq * 8 + 4);
;     float s = (a[0] + a[2]) + (b[0] + b[2]), q = (a[1] + a[3]) + (b[1] + b[3]);
;     s += bperm(s, lane ^ 16); q += bperm(q, lane ^ 16); s += bperm(s, lane ^ 32); q += bperm(q, lane ^ 32);
;     mu = s * (1.0f / 1024.0f); rstd = __builtin_amdgcn_rsqf(fmaxf(q * (1.0f / 1024.0f) - mu * mu, 0.f) + EPS);
;     DI void operator()(const f32x4 (&acc)[2][2][4][2], const pg8::Unit& u, int wr, int wc, int fr, int fq) const {
;         asm volatile("" : "+v"(fr), "+v"(fq));
;         const int row0 = u.pm * 256 + wr * 64 + fr, col0 = u.pn * 256 + wc * 32 + 8 * fq, lane = fq * 16 + fr;
; #pragma unroll
;         for (int ai = 0; ai < 2; ++ai)
; #pragma unroll
;             for (int m = 0; m < 4; ++m) { const int row = row0 + ai * 128 + m * 16; const size_t off = (size_t)row * DMODEL + col0; float mu, rstd; row_stats(STAT, row, fq, lane, mu, rstd);
; #pragma unroll
;                 for (int bj = 0; bj < 2; ++bj) { float p[8]; unpack8(*(const u32x4*)(XBin + off + bj * 128), p);
;                     const f32x4 g0 = *(const f32x4*)(g + col0 + bj * 128), g1 = *(const f32x4*)(g + col0 + bj * 128 + 4), b0 = *(const f32x4*)(b + col0 + bj * 128), b1 = *(const f32x4*)(b + col0 + bj * 128 + 4);
;                     float o[8];
; #pragma unroll
;                     for (int k = 0; k < 8; ++k) { const float gg = k < 4 ? g0[k & 3] : g1[k & 3], bb = k < 4 ? b0[k & 3] : b1[k & 3]; const float x1 = (p[k] - mu) * rstd * gg + bb; o[k] = x1 * ALPHA + acc[ai][bj][m][k >> 2][k & 3]; }
;                     if (out32) { *(f32x4*)(out32 + off + bj * 128) = (f32x4){o[0], o[1], o[2], o[3]}; *(f32x4*)(out32 + off + bj * 128 + 4) = (f32x4){o[4], o[5], o[6], o[7]}; }
;                     else *(u32x4*)(XBout + off + bj * 128) = pack8(o); }
.LBB0_1979:
	s_lshl_b32 s2, s95, 8
	v_mov_b32_e32 v140, v159
	v_mov_b32_e32 v141, v158
	s_add_i32 s2, s2, s58
	s_andn2_b64 vcc, exec, s[44:45]
	v_add_u32_e32 v146, s2, v141
	s_lshl_b32 s2, s15, 8
	s_or_b32 s2, s2, s82
	v_lshlrev_b32_e32 v144, 3, v140
	v_lshlrev_b32_e32 v141, 2, v141
	v_add_u32_e32 v148, s2, v144
	v_lshl_add_u32 v140, v140, 6, v141
	v_ashrrev_i32_e32 v147, 31, v146
	v_ashrrev_i32_e32 v149, 31, v148
	v_xor_b32_e32 v163, 64, v140
	v_xor_b32_e32 v162, 0x80, v140
	v_lshlrev_b64 v[140:141], 10, v[146:147]
	v_lshl_add_u64 v[156:157], v[140:141], 0, v[148:149]
	v_lshlrev_b64 v[140:141], 7, v[146:147]
	v_ashrrev_i32_e32 v145, 31, v144
	v_lshl_add_u64 v[140:141], s[36:37], 0, v[140:141]
	v_lshl_add_u64 v[150:151], v[144:145], 2, v[140:141]
	global_load_dwordx4 v[140:143], v[150:151], off offset:16
	s_nop 0
	global_load_dwordx4 v[150:153], v[150:151], off
	v_lshlrev_b64 v[184:185], 2, v[148:149]
	v_lshl_add_u64 v[182:183], s[20:21], 0, v[184:185]
	v_lshl_add_u64 v[184:185], s[22:23], 0, v[184:185]
	global_load_dwordx4 v[220:223], v[182:183], off offset:16
	global_load_dwordx4 v[224:227], v[182:183], off
	global_load_dwordx4 v[228:231], v[184:185], off offset:16
	global_load_dwordx4 v[232:235], v[184:185], off
	global_load_dwordx4 v[242:245], v[182:183], off offset:528
	global_load_dwordx4 v[246:249], v[182:183], off offset:512
	global_load_dwordx4 v[250:253], v[184:185], off offset:528
	global_load_dwordx2 v[240:241], v[184:185], off offset:512
	global_load_dwordx2 v[186:187], v[184:185], off offset:520
	s_mov_b32 s2, 0x3a800000
	v_cndmask_b32_e64 v147, 0, 1, s[44:45]
	v_cmp_ne_u32_e64 s[18:19], 1, v147
	s_waitcnt vmcnt(9)
	v_pk_add_f32 v[140:141], v[140:141], v[142:143]
	v_pk_add_f32 v[150:151], v[150:151], v[152:153]
	s_nop 0
	v_pk_add_f32 v[140:141], v[150:151], v[140:141]
	ds_bpermute_b32 v142, v163, v140
	ds_bpermute_b32 v143, v163, v141
	v_lshl_add_u64 v[150:151], v[156:157], 1, s[26:27]
	global_load_dwordx4 v[164:167], v[150:151], off
	global_load_dwordx4 v[236:239], v[150:151], off offset:256
	v_lshl_add_u64 v[156:157], v[156:157], 2, s[28:29]
	s_waitcnt lgkmcnt(0)
	v_pk_add_f32 v[140:141], v[140:141], v[142:143]
	ds_bpermute_b32 v142, v162, v140
	ds_bpermute_b32 v143, v162, v141
	s_waitcnt lgkmcnt(0)
	v_pk_add_f32 v[140:141], v[140:141], v[142:143]
	s_nop 0
	v_pk_mul_f32 v[152:153], v[140:141], s[2:3] op_sel_hi:[1,0]
	s_waitcnt vmcnt(0)
	v_lshlrev_b32_e32 v184, 16, v164
	v_fma_f32 v140, -v152, v152, v153
	v_max_f32_e32 v140, 0, v140
	v_add_f32_e32 v140, 0x3727c5ac, v140
	v_rsq_f32_e32 v154, v140
	v_lshlrev_b64 v[140:141], 2, v[148:149]
	v_lshl_add_u64 v[142:143], s[20:21], 0, v[140:141]
	v_lshl_add_u64 v[140:141], s[22:23], 0, v[140:141]
	s_nop 1
	v_mov_b32_e32 v168, v220
	v_mov_b32_e32 v169, v221
	v_mov_b32_e32 v170, v222
	v_mov_b32_e32 v171, v223
	v_mov_b32_e32 v172, v224
	v_mov_b32_e32 v173, v225
	v_mov_b32_e32 v174, v226
	v_mov_b32_e32 v175, v227
	v_mov_b32_e32 v176, v228
	v_mov_b32_e32 v177, v229
	v_mov_b32_e32 v178, v230
	v_mov_b32_e32 v179, v231
	v_mov_b32_e32 v180, v232
	v_mov_b32_e32 v181, v233
	v_mov_b32_e32 v182, v234
	v_mov_b32_e32 v183, v235
	v_and_b32_e32 v185, 0xffff0000, v164
	v_lshlrev_b32_e32 v164, 16, v165
	v_and_b32_e32 v165, 0xffff0000, v165
	v_pk_add_f32 v[164:165], v[164:165], v[152:153] op_sel_hi:[1,0] neg_lo:[0,1] neg_hi:[0,1]
	v_pk_add_f32 v[184:185], v[184:185], v[152:153] op_sel_hi:[1,0] neg_lo:[0,1] neg_hi:[0,1]
	v_pk_mul_f32 v[164:165], v[164:165], v[154:155] op_sel_hi:[1,0]
	v_pk_mul_f32 v[184:185], v[184:185], v[154:155] op_sel_hi:[1,0]
	s_waitcnt vmcnt(0)
	v_pk_fma_f32 v[164:165], v[174:175], v[164:165], v[182:183]
	s_nop 0
	v_pk_fma_f32 v[128:129], v[164:165], s[86:87], v[128:129] op_sel_hi:[1,0,1]
	v_lshlrev_b32_e32 v164, 16, v166
	v_and_b32_e32 v165, 0xffff0000, v166
	v_pk_add_f32 v[164:165], v[164:165], v[152:153] op_sel_hi:[1,0] neg_lo:[0,1] neg_hi:[0,1]
	v_pk_fma_f32 v[172:173], v[172:173], v[184:185], v[180:181]
	v_pk_mul_f32 v[164:165], v[164:165], v[154:155] op_sel_hi:[1,0]
	v_pk_fma_f32 v[126:127], v[172:173], s[86:87], v[126:127] op_sel_hi:[1,0,1]
	v_pk_fma_f32 v[164:165], v[168:169], v[164:165], v[176:177]
	s_nop 0
	v_pk_fma_f32 v[122:123], v[164:165], s[86:87], v[122:123] op_sel_hi:[1,0,1]
	v_lshlrev_b32_e32 v164, 16, v167
	v_and_b32_e32 v165, 0xffff0000, v167
	v_pk_add_f32 v[164:165], v[164:165], v[152:153] op_sel_hi:[1,0] neg_lo:[0,1] neg_hi:[0,1]
	s_nop 0
	v_pk_mul_f32 v[164:165], v[164:165], v[154:155] op_sel_hi:[1,0]
	s_nop 0
	v_pk_fma_f32 v[164:165], v[170:171], v[164:165], v[178:179]
	s_nop 0
	v_pk_fma_f32 v[124:125], v[164:165], s[86:87], v[124:125] op_sel_hi:[1,0,1]
	s_cbranch_vccnz .LBB0_1981
	s_mov_b64 s[2:3], 0
	global_store_dwordx4 v[156:157], v[126:129], off
	global_store_dwordx4 v[156:157], v[122:125], off offset:16
	s_branch .LBB0_1982

; DI u32x4 pack8(const float (&v)[8]) { u32x4 w; w.x = pk2(v[0], v[1]); w.y = pk2(v[2], v[3]); w.z = pk2(v[4], v[5]); w.w = pk2(v[6], v[7]); return w; }
;     DI void operator()(const f32x4 (&acc)[2][2][4][2], const pg8::Unit& u, int wr, int wc, int fr, int fq) const {
;     ...
;                 for (int bj = 0; bj < 2; ++bj) { float p[8]; unpack8(*(const u32x4*)(XBin + off + bj * 128), p);
;                     const f32x4 g0 = *(const f32x4*)(g + col0 + bj * 128), g1 = *(const f32x4*)(g + col0 + bj * 128 + 4), b0 = *(const f32x4*)(b + col0 + bj * 128), b1 = *(const f32x4*)(b + col0 + bj * 128 + 4);
;                     float o[8];
; #pragma unroll
;                     for (int k = 0; k < 8; ++k) { const float gg = k < 4 ? g0[k & 3] : g1[k & 3], bb = k < 4 ? b0[k & 3] : b1[k & 3]; const float x1 = (p[k] - mu) * rstd * gg + bb; o[k] = x1 * ALPHA + acc[ai][bj][m][k >> 2][k & 3]; }
;                     if (out32) { *(f32x4*)(out32 + off + bj * 128) = (f32x4){o[0], o[1], o[2], o[3]}; *(f32x4*)(out32 + off + bj * 128 + 4) = (f32x4){o[4], o[5], o[6], o[7]}; }
;                     else *(u32x4*)(XBout + off + bj * 128) = pack8(o); }
.LBB0_1984:
	s_nop 1
	v_mov_b32_e32 v122, v236
	v_mov_b32_e32 v123, v237
	v_mov_b32_e32 v124, v238
	v_mov_b32_e32 v125, v239
	s_nop 0
	s_nop 1
	v_mov_b32_e32 v126, v242
	v_mov_b32_e32 v127, v243
	v_mov_b32_e32 v128, v244
	v_mov_b32_e32 v129, v245
	v_mov_b32_e32 v164, v246
	v_mov_b32_e32 v165, v247
	v_mov_b32_e32 v166, v248
	v_mov_b32_e32 v167, v249
	v_mov_b32_e32 v168, v250
	v_mov_b32_e32 v169, v251
	v_mov_b32_e32 v170, v252
	v_mov_b32_e32 v171, v253
	v_mov_b32_e32 v172, v240
	v_mov_b32_e32 v173, v241
	v_mov_b32_e32 v174, v186
	v_mov_b32_e32 v175, v187
	v_mov_b32_e32 v153, v152
	v_mov_b32_e32 v155, v154
	s_and_b64 vcc, exec, s[18:19]
	s_nop 0
	v_lshlrev_b32_e32 v176, 16, v122
	v_and_b32_e32 v177, 0xffff0000, v122
	v_lshlrev_b32_e32 v122, 16, v123
	v_and_b32_e32 v123, 0xffff0000, v123
	v_pk_add_f32 v[122:123], v[122:123], v[152:153] neg_lo:[0,1] neg_hi:[0,1]
	v_pk_add_f32 v[176:177], v[176:177], v[152:153] neg_lo:[0,1] neg_hi:[0,1]
	v_pk_mul_f32 v[122:123], v[154:155], v[122:123]
	v_pk_mul_f32 v[176:177], v[154:155], v[176:177]
	s_nop 0
	v_pk_fma_f32 v[122:123], v[166:167], v[122:123], v[174:175]
	v_pk_fma_f32 v[164:165], v[164:165], v[176:177], v[172:173]
	v_pk_fma_f32 v[120:121], v[122:123], s[86:87], v[120:121] op_sel_hi:[1,0,1]
	v_lshlrev_b32_e32 v122, 16, v124
	v_and_b32_e32 v123, 0xffff0000, v124
	v_pk_add_f32 v[122:123], v[122:123], v[152:153] neg_lo:[0,1] neg_hi:[0,1]
	v_pk_fma_f32 v[118:119], v[164:165], s[86:87], v[118:119] op_sel_hi:[1,0,1]
	v_pk_mul_f32 v[122:123], v[154:155], v[122:123]
	s_nop 0
	v_pk_fma_f32 v[122:123], v[126:127], v[122:123], v[168:169]
	s_nop 0
	v_pk_fma_f32 v[114:115], v[122:123], s[86:87], v[114:115] op_sel_hi:[1,0,1]
	v_lshlrev_b32_e32 v122, 16, v125
	v_and_b32_e32 v123, 0xffff0000, v125
	v_pk_add_f32 v[122:123], v[122:123], v[152:153] neg_lo:[0,1] neg_hi:[0,1]
	s_nop 0
	v_pk_mul_f32 v[122:123], v[154:155], v[122:123]
	s_nop 0
	v_pk_fma_f32 v[122:123], v[128:129], v[122:123], v[170:171]
	s_nop 0
	v_pk_fma_f32 v[116:117], v[122:123], s[86:87], v[116:117] op_sel_hi:[1,0,1]
	s_cbranch_vccnz .LBB0_2032
	global_store_dwordx4 v[156:157], v[118:121], off offset:512
	global_store_dwordx4 v[156:157], v[114:117], off offset:528
	s_cbranch_execnz .LBB0_1987

; DI u32x4 pack8(const float (&v)[8]) { u32x4 w; w.x = pk2(v[0], v[1]); w.y = pk2(v[2], v[3]); w.z = pk2(v[4], v[5]); w.w = pk2(v[6], v[7]); return w; }
;     DI void operator()(const f32x4 (&acc)[2][2][4][2], const pg8::Unit& u, int wr, int wc, int fr, int fq) const {
;     ...
;                 for (int bj = 0; bj < 2; ++bj) { float p[8]; unpack8(*(const u32x4*)(XBin + off + bj * 128), p);
;                     const f32x4 g0 = *(const f32x4*)(g + col0 + bj * 128), g1 = *(const f32x4*)(g + col0 + bj * 128 + 4), b0 = *(const f32x4*)(b + col0 + bj * 128), b1 = *(const f32x4*)(b + col0 + bj * 128 + 4);
;                     float o[8];
; #pragma unroll
;                     for (int k = 0; k < 8; ++k) { const float gg = k < 4 ? g0[k & 3] : g1[k & 3], bb = k < 4 ? b0[k & 3] : b1[k & 3]; const float x1 = (p[k] - mu) * rstd * gg + bb; o[k] = x1 * ALPHA + acc[ai][bj][m][k >> 2][k & 3]; }
;                     if (out32) { *(f32x4*)(out32 + off + bj * 128) = (f32x4){o[0], o[1], o[2], o[3]}; *(f32x4*)(out32 + off + bj * 128 + 4) = (f32x4){o[4], o[5], o[6], o[7]}; }
;                     else *(u32x4*)(XBout + off + bj * 128) = pack8(o); }
.LBB0_1990:
	s_nop 1
	v_mov_b32_e32 v106, v174
	v_mov_b32_e32 v107, v175
	v_mov_b32_e32 v108, v176
	v_mov_b32_e32 v109, v177
	s_nop 0
	s_nop 1
	v_mov_b32_e32 v110, v242
	v_mov_b32_e32 v111, v243
	v_mov_b32_e32 v112, v244
	v_mov_b32_e32 v113, v245
	v_mov_b32_e32 v122, v246
	v_mov_b32_e32 v123, v247
	v_mov_b32_e32 v124, v248
	v_mov_b32_e32 v125, v249
	v_mov_b32_e32 v126, v250
	v_mov_b32_e32 v127, v251
	v_mov_b32_e32 v128, v252
	v_mov_b32_e32 v129, v253
	v_mov_b32_e32 v150, v240
	v_mov_b32_e32 v151, v241
	v_mov_b32_e32 v152, v186
	v_mov_b32_e32 v153, v187
	v_mov_b32_e32 v117, v116
	v_mov_b32_e32 v119, v118
	s_and_b64 vcc, exec, s[18:19]
	s_nop 0
	v_lshlrev_b32_e32 v154, 16, v106
	v_and_b32_e32 v155, 0xffff0000, v106
	v_lshlrev_b32_e32 v106, 16, v107
	v_and_b32_e32 v107, 0xffff0000, v107
	v_pk_add_f32 v[106:107], v[106:107], v[116:117] neg_lo:[0,1] neg_hi:[0,1]
	v_pk_add_f32 v[154:155], v[154:155], v[116:117] neg_lo:[0,1] neg_hi:[0,1]
	v_pk_mul_f32 v[106:107], v[118:119], v[106:107]
	v_pk_mul_f32 v[154:155], v[118:119], v[154:155]
	s_nop 0
	v_pk_fma_f32 v[106:107], v[124:125], v[106:107], v[152:153]
	v_pk_fma_f32 v[122:123], v[122:123], v[154:155], v[150:151]
	v_pk_fma_f32 v[104:105], v[106:107], s[86:87], v[104:105] op_sel_hi:[1,0,1]
	v_lshlrev_b32_e32 v106, 16, v108
	v_and_b32_e32 v107, 0xffff0000, v108
	v_pk_add_f32 v[106:107], v[106:107], v[116:117] neg_lo:[0,1] neg_hi:[0,1]
	v_pk_fma_f32 v[102:103], v[122:123], s[86:87], v[102:103] op_sel_hi:[1,0,1]
	v_pk_mul_f32 v[106:107], v[118:119], v[106:107]
	s_nop 0
	v_pk_fma_f32 v[106:107], v[110:111], v[106:107], v[126:127]
	s_nop 0
	v_pk_fma_f32 v[98:99], v[106:107], s[86:87], v[98:99] op_sel_hi:[1,0,1]
	v_lshlrev_b32_e32 v106, 16, v109
	v_and_b32_e32 v107, 0xffff0000, v109
	v_pk_add_f32 v[106:107], v[106:107], v[116:117] neg_lo:[0,1] neg_hi:[0,1]
	s_nop 0
	v_pk_mul_f32 v[106:107], v[118:119], v[106:107]
	s_nop 0
	v_pk_fma_f32 v[106:107], v[112:113], v[106:107], v[128:129]
	s_nop 0
	v_pk_fma_f32 v[100:101], v[106:107], s[86:87], v[100:101] op_sel_hi:[1,0,1]
	s_cbranch_vccnz .LBB0_2034
	global_store_dwordx4 v[120:121], v[102:105], off offset:512
	global_store_dwordx4 v[120:121], v[98:101], off offset:528
	s_cbranch_execnz .LBB0_1993

; DI u32x4 pack8(const float (&v)[8]) { u32x4 w; w.x = pk2(v[0], v[1]); w.y = pk2(v[2], v[3]); w.z = pk2(v[4], v[5]); w.w = pk2(v[6], v[7]); return w; }
;     DI void operator()(const f32x4 (&acc)[2][2][4][2], const pg8::Unit& u, int wr, int wc, int fr, int fq) const {
;     ...
;                 for (int bj = 0; bj < 2; ++bj) { float p[8]; unpack8(*(const u32x4*)(XBin + off + bj * 128), p);
;                     const f32x4 g0 = *(const f32x4*)(g + col0 + bj * 128), g1 = *(const f32x4*)(g + col0 + bj * 128 + 4), b0 = *(const f32x4*)(b + col0 + bj * 128), b1 = *(const f32x4*)(b + col0 + bj * 128 + 4);
;                     float o[8];
; #pragma unroll
;                     for (int k = 0; k < 8; ++k) { const float gg = k < 4 ? g0[k & 3] : g1[k & 3], bb = k < 4 ? b0[k & 3] : b1[k & 3]; const float x1 = (p[k] - mu) * rstd * gg + bb; o[k] = x1 * ALPHA + acc[ai][bj][m][k >> 2][k & 3]; }
;                     if (out32) { *(f32x4*)(out32 + off + bj * 128) = (f32x4){o[0], o[1], o[2], o[3]}; *(f32x4*)(out32 + off + bj * 128 + 4) = (f32x4){o[4], o[5], o[6], o[7]}; }
;                     else *(u32x4*)(XBout + off + bj * 128) = pack8(o); }
.LBB0_1996:
	s_nop 1
	v_mov_b32_e32 v90, v174
	v_mov_b32_e32 v91, v175
	v_mov_b32_e32 v92, v176
	v_mov_b32_e32 v93, v177
	s_nop 0
	s_nop 1
	v_mov_b32_e32 v94, v242
	v_mov_b32_e32 v95, v243
	v_mov_b32_e32 v96, v244
	v_mov_b32_e32 v97, v245
	v_mov_b32_e32 v106, v246
	v_mov_b32_e32 v107, v247
	v_mov_b32_e32 v108, v248
	v_mov_b32_e32 v109, v249
	v_mov_b32_e32 v110, v250
	v_mov_b32_e32 v111, v251
	v_mov_b32_e32 v112, v252
	v_mov_b32_e32 v113, v253
	v_mov_b32_e32 v114, v240
	v_mov_b32_e32 v115, v241
	v_mov_b32_e32 v116, v186
	v_mov_b32_e32 v117, v187
	v_mov_b32_e32 v101, v100
	v_mov_b32_e32 v103, v102
	s_and_b64 vcc, exec, s[18:19]
	s_nop 0
	v_lshlrev_b32_e32 v118, 16, v90
	v_and_b32_e32 v119, 0xffff0000, v90
	v_lshlrev_b32_e32 v90, 16, v91
	v_and_b32_e32 v91, 0xffff0000, v91
	v_pk_add_f32 v[90:91], v[90:91], v[100:101] neg_lo:[0,1] neg_hi:[0,1]
	v_pk_add_f32 v[118:119], v[118:119], v[100:101] neg_lo:[0,1] neg_hi:[0,1]
	v_pk_mul_f32 v[90:91], v[102:103], v[90:91]
	v_pk_mul_f32 v[118:119], v[102:103], v[118:119]
	s_nop 0
	v_pk_fma_f32 v[90:91], v[108:109], v[90:91], v[116:117]
	v_pk_fma_f32 v[106:107], v[106:107], v[118:119], v[114:115]
	v_pk_fma_f32 v[88:89], v[90:91], s[86:87], v[88:89] op_sel_hi:[1,0,1]
	v_lshlrev_b32_e32 v90, 16, v92
	v_and_b32_e32 v91, 0xffff0000, v92
	v_pk_add_f32 v[90:91], v[90:91], v[100:101] neg_lo:[0,1] neg_hi:[0,1]
	v_pk_fma_f32 v[86:87], v[106:107], s[86:87], v[86:87] op_sel_hi:[1,0,1]
	v_pk_mul_f32 v[90:91], v[102:103], v[90:91]
	s_nop 0
	v_pk_fma_f32 v[90:91], v[94:95], v[90:91], v[110:111]
	s_nop 0
	v_pk_fma_f32 v[82:83], v[90:91], s[86:87], v[82:83] op_sel_hi:[1,0,1]
	v_lshlrev_b32_e32 v90, 16, v93
	v_and_b32_e32 v91, 0xffff0000, v93
	v_pk_add_f32 v[90:91], v[90:91], v[100:101] neg_lo:[0,1] neg_hi:[0,1]
	s_nop 0
	v_pk_mul_f32 v[90:91], v[102:103], v[90:91]
	s_nop 0
	v_pk_fma_f32 v[90:91], v[96:97], v[90:91], v[112:113]
	s_nop 0
	v_pk_fma_f32 v[84:85], v[90:91], s[86:87], v[84:85] op_sel_hi:[1,0,1]
	s_cbranch_vccnz .LBB0_2036
	global_store_dwordx4 v[104:105], v[86:89], off offset:512
	global_store_dwordx4 v[104:105], v[82:85], off offset:528
	s_cbranch_execnz .LBB0_1999

; DI u32x4 pack8(const float (&v)[8]) { u32x4 w; w.x = pk2(v[0], v[1]); w.y = pk2(v[2], v[3]); w.z = pk2(v[4], v[5]); w.w = pk2(v[6], v[7]); return w; }
;     DI void operator()(const f32x4 (&acc)[2][2][4][2], const pg8::Unit& u, int wr, int wc, int fr, int fq) const {
;     ...
;                 for (int bj = 0; bj < 2; ++bj) { float p[8]; unpack8(*(const u32x4*)(XBin + off + bj * 128), p);
;                     const f32x4 g0 = *(const f32x4*)(g + col0 + bj * 128), g1 = *(const f32x4*)(g + col0 + bj * 128 + 4), b0 = *(const f32x4*)(b + col0 + bj * 128), b1 = *(const f32x4*)(b + col0 + bj * 128 + 4);
;                     float o[8];
; #pragma unroll
;                     for (int k = 0; k < 8; ++k) { const float gg = k < 4 ? g0[k & 3] : g1[k & 3], bb = k < 4 ? b0[k & 3] : b1[k & 3]; const float x1 = (p[k] - mu) * rstd * gg + bb; o[k] = x1 * ALPHA + acc[ai][bj][m][k >> 2][k & 3]; }
;                     if (out32) { *(f32x4*)(out32 + off + bj * 128) = (f32x4){o[0], o[1], o[2], o[3]}; *(f32x4*)(out32 + off + bj * 128 + 4) = (f32x4){o[4], o[5], o[6], o[7]}; }
;                     else *(u32x4*)(XBout + off + bj * 128) = pack8(o); }
.LBB0_2002:
	s_nop 1
	v_mov_b32_e32 v74, v174
	v_mov_b32_e32 v75, v175
	v_mov_b32_e32 v76, v176
	v_mov_b32_e32 v77, v177
	s_nop 0
	s_nop 1
	v_mov_b32_e32 v78, v242
	v_mov_b32_e32 v79, v243
	v_mov_b32_e32 v80, v244
	v_mov_b32_e32 v81, v245
	v_mov_b32_e32 v90, v246
	v_mov_b32_e32 v91, v247
	v_mov_b32_e32 v92, v248
	v_mov_b32_e32 v93, v249
	v_mov_b32_e32 v94, v250
	v_mov_b32_e32 v95, v251
	v_mov_b32_e32 v96, v252
	v_mov_b32_e32 v97, v253
	v_mov_b32_e32 v98, v240
	v_mov_b32_e32 v99, v241
	v_mov_b32_e32 v100, v186
	v_mov_b32_e32 v101, v187
	v_mov_b32_e32 v85, v84
	v_mov_b32_e32 v87, v86
	s_and_b64 vcc, exec, s[18:19]
	s_nop 0
	v_lshlrev_b32_e32 v102, 16, v74
	v_and_b32_e32 v103, 0xffff0000, v74
	v_lshlrev_b32_e32 v74, 16, v75
	v_and_b32_e32 v75, 0xffff0000, v75
	v_pk_add_f32 v[74:75], v[74:75], v[84:85] neg_lo:[0,1] neg_hi:[0,1]
	v_pk_add_f32 v[102:103], v[102:103], v[84:85] neg_lo:[0,1] neg_hi:[0,1]
	v_pk_mul_f32 v[74:75], v[86:87], v[74:75]
	v_pk_mul_f32 v[102:103], v[86:87], v[102:103]
	s_nop 0
	v_pk_fma_f32 v[74:75], v[92:93], v[74:75], v[100:101]
	v_pk_fma_f32 v[90:91], v[90:91], v[102:103], v[98:99]
	v_pk_fma_f32 v[72:73], v[74:75], s[86:87], v[72:73] op_sel_hi:[1,0,1]
	v_lshlrev_b32_e32 v74, 16, v76
	v_and_b32_e32 v75, 0xffff0000, v76
	v_pk_add_f32 v[74:75], v[74:75], v[84:85] neg_lo:[0,1] neg_hi:[0,1]
	v_pk_fma_f32 v[70:71], v[90:91], s[86:87], v[70:71] op_sel_hi:[1,0,1]
	v_pk_mul_f32 v[74:75], v[86:87], v[74:75]
	s_nop 0
	v_pk_fma_f32 v[74:75], v[78:79], v[74:75], v[94:95]
	s_nop 0
	v_pk_fma_f32 v[66:67], v[74:75], s[86:87], v[66:67] op_sel_hi:[1,0,1]
	v_lshlrev_b32_e32 v74, 16, v77
	v_and_b32_e32 v75, 0xffff0000, v77
	v_pk_add_f32 v[74:75], v[74:75], v[84:85] neg_lo:[0,1] neg_hi:[0,1]
	s_nop 0
	v_pk_mul_f32 v[74:75], v[86:87], v[74:75]
	s_nop 0
	v_pk_fma_f32 v[74:75], v[80:81], v[74:75], v[96:97]
	s_nop 0
	v_pk_fma_f32 v[68:69], v[74:75], s[86:87], v[68:69] op_sel_hi:[1,0,1]
	s_cbranch_vccnz .LBB0_2038
	global_store_dwordx4 v[88:89], v[70:73], off offset:512
	global_store_dwordx4 v[88:89], v[66:69], off offset:528
	s_cbranch_execnz .LBB0_2005

; DI u32x4 pack8(const float (&v)[8]) { u32x4 w; w.x = pk2(v[0], v[1]); w.y = pk2(v[2], v[3]); w.z = pk2(v[4], v[5]); w.w = pk2(v[6], v[7]); return w; }
;     DI void operator()(const f32x4 (&acc)[2][2][4][2], const pg8::Unit& u, int wr, int wc, int fr, int fq) const {
;     ...
;                 for (int bj = 0; bj < 2; ++bj) { float p[8]; unpack8(*(const u32x4*)(XBin + off + bj * 128), p);
;                     const f32x4 g0 = *(const f32x4*)(g + col0 + bj * 128), g1 = *(const f32x4*)(g + col0 + bj * 128 + 4), b0 = *(const f32x4*)(b + col0 + bj * 128), b1 = *(const f32x4*)(b + col0 + bj * 128 + 4);
;                     float o[8];
; #pragma unroll
;                     for (int k = 0; k < 8; ++k) { const float gg = k < 4 ? g0[k & 3] : g1[k & 3], bb = k < 4 ? b0[k & 3] : b1[k & 3]; const float x1 = (p[k] - mu) * rstd * gg + bb; o[k] = x1 * ALPHA + acc[ai][bj][m][k >> 2][k & 3]; }
;                     if (out32) { *(f32x4*)(out32 + off + bj * 128) = (f32x4){o[0], o[1], o[2], o[3]}; *(f32x4*)(out32 + off + bj * 128 + 4) = (f32x4){o[4], o[5], o[6], o[7]}; }
;                     else *(u32x4*)(XBout + off + bj * 128) = pack8(o); }
.LBB0_2008:
	s_nop 1
	v_mov_b32_e32 v58, v174
	v_mov_b32_e32 v59, v175
	v_mov_b32_e32 v60, v176
	v_mov_b32_e32 v61, v177
	s_nop 0
	s_nop 1
	v_mov_b32_e32 v62, v242
	v_mov_b32_e32 v63, v243
	v_mov_b32_e32 v64, v244
	v_mov_b32_e32 v65, v245
	v_mov_b32_e32 v74, v246
	v_mov_b32_e32 v75, v247
	v_mov_b32_e32 v76, v248
	v_mov_b32_e32 v77, v249
	v_mov_b32_e32 v78, v250
	v_mov_b32_e32 v79, v251
	v_mov_b32_e32 v80, v252
	v_mov_b32_e32 v81, v253
	v_mov_b32_e32 v82, v240
	v_mov_b32_e32 v83, v241
	v_mov_b32_e32 v84, v186
	v_mov_b32_e32 v85, v187
	v_mov_b32_e32 v69, v68
	v_mov_b32_e32 v71, v70
	s_and_b64 vcc, exec, s[18:19]
	s_nop 0
	v_lshlrev_b32_e32 v86, 16, v58
	v_and_b32_e32 v87, 0xffff0000, v58
	v_lshlrev_b32_e32 v58, 16, v59
	v_and_b32_e32 v59, 0xffff0000, v59
	v_pk_add_f32 v[58:59], v[58:59], v[68:69] neg_lo:[0,1] neg_hi:[0,1]
	v_pk_add_f32 v[86:87], v[86:87], v[68:69] neg_lo:[0,1] neg_hi:[0,1]
	v_pk_mul_f32 v[58:59], v[70:71], v[58:59]
	v_pk_mul_f32 v[86:87], v[70:71], v[86:87]
	s_nop 0
	v_pk_fma_f32 v[58:59], v[76:77], v[58:59], v[84:85]
	v_pk_fma_f32 v[74:75], v[74:75], v[86:87], v[82:83]
	v_pk_fma_f32 v[56:57], v[58:59], s[86:87], v[56:57] op_sel_hi:[1,0,1]
	v_lshlrev_b32_e32 v58, 16, v60
	v_and_b32_e32 v59, 0xffff0000, v60
	v_pk_add_f32 v[58:59], v[58:59], v[68:69] neg_lo:[0,1] neg_hi:[0,1]
	v_pk_fma_f32 v[54:55], v[74:75], s[86:87], v[54:55] op_sel_hi:[1,0,1]
	v_pk_mul_f32 v[58:59], v[70:71], v[58:59]
	s_nop 0
	v_pk_fma_f32 v[58:59], v[62:63], v[58:59], v[78:79]
	s_nop 0
	v_pk_fma_f32 v[50:51], v[58:59], s[86:87], v[50:51] op_sel_hi:[1,0,1]
	v_lshlrev_b32_e32 v58, 16, v61
	v_and_b32_e32 v59, 0xffff0000, v61
	v_pk_add_f32 v[58:59], v[58:59], v[68:69] neg_lo:[0,1] neg_hi:[0,1]
	s_nop 0
	v_pk_mul_f32 v[58:59], v[70:71], v[58:59]
	s_nop 0
	v_pk_fma_f32 v[58:59], v[64:65], v[58:59], v[80:81]
	s_nop 0
	v_pk_fma_f32 v[52:53], v[58:59], s[86:87], v[52:53] op_sel_hi:[1,0,1]
	s_cbranch_vccnz .LBB0_2040
	global_store_dwordx4 v[72:73], v[54:57], off offset:512
	global_store_dwordx4 v[72:73], v[50:53], off offset:528
	s_cbranch_execnz .LBB0_2011

; DI u32x4 pack8(const float (&v)[8]) { u32x4 w; w.x = pk2(v[0], v[1]); w.y = pk2(v[2], v[3]); w.z = pk2(v[4], v[5]); w.w = pk2(v[6], v[7]); return w; }
;     DI void operator()(const f32x4 (&acc)[2][2][4][2], const pg8::Unit& u, int wr, int wc, int fr, int fq) const {
;     ...
;                 for (int bj = 0; bj < 2; ++bj) { float p[8]; unpack8(*(const u32x4*)(XBin + off + bj * 128), p);
;                     const f32x4 g0 = *(const f32x4*)(g + col0 + bj * 128), g1 = *(const f32x4*)(g + col0 + bj * 128 + 4), b0 = *(const f32x4*)(b + col0 + bj * 128), b1 = *(const f32x4*)(b + col0 + bj * 128 + 4);
;                     float o[8];
; #pragma unroll
;                     for (int k = 0; k < 8; ++k) { const float gg = k < 4 ? g0[k & 3] : g1[k & 3], bb = k < 4 ? b0[k & 3] : b1[k & 3]; const float x1 = (p[k] - mu) * rstd * gg + bb; o[k] = x1 * ALPHA + acc[ai][bj][m][k >> 2][k & 3]; }
;                     if (out32) { *(f32x4*)(out32 + off + bj * 128) = (f32x4){o[0], o[1], o[2], o[3]}; *(f32x4*)(out32 + off + bj * 128 + 4) = (f32x4){o[4], o[5], o[6], o[7]}; }
;                     else *(u32x4*)(XBout + off + bj * 128) = pack8(o); }
.LBB0_2014:
	s_nop 1
	v_mov_b32_e32 v42, v174
	v_mov_b32_e32 v43, v175
	v_mov_b32_e32 v44, v176
	v_mov_b32_e32 v45, v177
	s_nop 0
	s_nop 1
	v_mov_b32_e32 v46, v242
	v_mov_b32_e32 v47, v243
	v_mov_b32_e32 v48, v244
	v_mov_b32_e32 v49, v245
	v_mov_b32_e32 v58, v246
	v_mov_b32_e32 v59, v247
	v_mov_b32_e32 v60, v248
	v_mov_b32_e32 v61, v249
	v_mov_b32_e32 v62, v250
	v_mov_b32_e32 v63, v251
	v_mov_b32_e32 v64, v252
	v_mov_b32_e32 v65, v253
	v_mov_b32_e32 v66, v240
	v_mov_b32_e32 v67, v241
	v_mov_b32_e32 v68, v186
	v_mov_b32_e32 v69, v187
	v_mov_b32_e32 v53, v52
	v_mov_b32_e32 v55, v54
	s_and_b64 vcc, exec, s[18:19]
	s_nop 0
	v_lshlrev_b32_e32 v70, 16, v42
	v_and_b32_e32 v71, 0xffff0000, v42
	v_lshlrev_b32_e32 v42, 16, v43
	v_and_b32_e32 v43, 0xffff0000, v43
	v_pk_add_f32 v[42:43], v[42:43], v[52:53] neg_lo:[0,1] neg_hi:[0,1]
	v_pk_add_f32 v[70:71], v[70:71], v[52:53] neg_lo:[0,1] neg_hi:[0,1]
	v_pk_mul_f32 v[42:43], v[54:55], v[42:43]
	v_pk_mul_f32 v[70:71], v[54:55], v[70:71]
	s_nop 0
	v_pk_fma_f32 v[42:43], v[60:61], v[42:43], v[68:69]
	v_pk_fma_f32 v[58:59], v[58:59], v[70:71], v[66:67]
	v_pk_fma_f32 v[40:41], v[42:43], s[86:87], v[40:41] op_sel_hi:[1,0,1]
	v_lshlrev_b32_e32 v42, 16, v44
	v_and_b32_e32 v43, 0xffff0000, v44
	v_pk_add_f32 v[42:43], v[42:43], v[52:53] neg_lo:[0,1] neg_hi:[0,1]
	v_pk_fma_f32 v[38:39], v[58:59], s[86:87], v[38:39] op_sel_hi:[1,0,1]
	v_pk_mul_f32 v[42:43], v[54:55], v[42:43]
	s_nop 0
	v_pk_fma_f32 v[42:43], v[46:47], v[42:43], v[62:63]
	s_nop 0
	v_pk_fma_f32 v[34:35], v[42:43], s[86:87], v[34:35] op_sel_hi:[1,0,1]
	v_lshlrev_b32_e32 v42, 16, v45
	v_and_b32_e32 v43, 0xffff0000, v45
	v_pk_add_f32 v[42:43], v[42:43], v[52:53] neg_lo:[0,1] neg_hi:[0,1]
	s_nop 0
	v_pk_mul_f32 v[42:43], v[54:55], v[42:43]
	s_nop 0
	v_pk_fma_f32 v[42:43], v[48:49], v[42:43], v[64:65]
	s_nop 0
	v_pk_fma_f32 v[36:37], v[42:43], s[86:87], v[36:37] op_sel_hi:[1,0,1]
	s_cbranch_vccnz .LBB0_2042
	global_store_dwordx4 v[56:57], v[38:41], off offset:512
	global_store_dwordx4 v[56:57], v[34:37], off offset:528
	s_cbranch_execnz .LBB0_2017

; DI u32x4 pack8(const float (&v)[8]) { u32x4 w; w.x = pk2(v[0], v[1]); w.y = pk2(v[2], v[3]); w.z = pk2(v[4], v[5]); w.w = pk2(v[6], v[7]); return w; }
;     DI void operator()(const f32x4 (&acc)[2][2][4][2], const pg8::Unit& u, int wr, int wc, int fr, int fq) const {
;     ...
;                 for (int bj = 0; bj < 2; ++bj) { float p[8]; unpack8(*(const u32x4*)(XBin + off + bj * 128), p);
;                     const f32x4 g0 = *(const f32x4*)(g + col0 + bj * 128), g1 = *(const f32x4*)(g + col0 + bj * 128 + 4), b0 = *(const f32x4*)(b + col0 + bj * 128), b1 = *(const f32x4*)(b + col0 + bj * 128 + 4);
;                     float o[8];
; #pragma unroll
;                     for (int k = 0; k < 8; ++k) { const float gg = k < 4 ? g0[k & 3] : g1[k & 3], bb = k < 4 ? b0[k & 3] : b1[k & 3]; const float x1 = (p[k] - mu) * rstd * gg + bb; o[k] = x1 * ALPHA + acc[ai][bj][m][k >> 2][k & 3]; }
;                     if (out32) { *(f32x4*)(out32 + off + bj * 128) = (f32x4){o[0], o[1], o[2], o[3]}; *(f32x4*)(out32 + off + bj * 128 + 4) = (f32x4){o[4], o[5], o[6], o[7]}; }
;                     else *(u32x4*)(XBout + off + bj * 128) = pack8(o); }
.LBB0_2020:
	s_nop 1
	v_mov_b32_e32 v26, v174
	v_mov_b32_e32 v27, v175
	v_mov_b32_e32 v28, v176
	v_mov_b32_e32 v29, v177
	s_nop 0
	s_nop 1
	v_mov_b32_e32 v30, v242
	v_mov_b32_e32 v31, v243
	v_mov_b32_e32 v32, v244
	v_mov_b32_e32 v33, v245
	v_mov_b32_e32 v42, v246
	v_mov_b32_e32 v43, v247
	v_mov_b32_e32 v44, v248
	v_mov_b32_e32 v45, v249
	v_mov_b32_e32 v46, v250
	v_mov_b32_e32 v47, v251
	v_mov_b32_e32 v48, v252
	v_mov_b32_e32 v49, v253
	v_mov_b32_e32 v50, v240
	v_mov_b32_e32 v51, v241
	v_mov_b32_e32 v52, v186
	v_mov_b32_e32 v53, v187
	v_mov_b32_e32 v37, v36
	v_mov_b32_e32 v39, v38
	s_and_b64 vcc, exec, s[18:19]
	s_nop 0
	v_lshlrev_b32_e32 v54, 16, v26
	v_and_b32_e32 v55, 0xffff0000, v26
	v_lshlrev_b32_e32 v26, 16, v27
	v_and_b32_e32 v27, 0xffff0000, v27
	v_pk_add_f32 v[26:27], v[26:27], v[36:37] neg_lo:[0,1] neg_hi:[0,1]
	v_pk_add_f32 v[54:55], v[54:55], v[36:37] neg_lo:[0,1] neg_hi:[0,1]
	v_pk_mul_f32 v[26:27], v[38:39], v[26:27]
	v_pk_mul_f32 v[54:55], v[38:39], v[54:55]
	s_nop 0
	v_pk_fma_f32 v[26:27], v[44:45], v[26:27], v[52:53]
	v_pk_fma_f32 v[42:43], v[42:43], v[54:55], v[50:51]
	v_pk_fma_f32 v[24:25], v[26:27], s[86:87], v[24:25] op_sel_hi:[1,0,1]
	v_lshlrev_b32_e32 v26, 16, v28
	v_and_b32_e32 v27, 0xffff0000, v28
	v_pk_add_f32 v[26:27], v[26:27], v[36:37] neg_lo:[0,1] neg_hi:[0,1]
	v_pk_fma_f32 v[22:23], v[42:43], s[86:87], v[22:23] op_sel_hi:[1,0,1]
	v_pk_mul_f32 v[26:27], v[38:39], v[26:27]
	s_nop 0
	v_pk_fma_f32 v[26:27], v[30:31], v[26:27], v[46:47]
	s_nop 0
	v_pk_fma_f32 v[18:19], v[26:27], s[86:87], v[18:19] op_sel_hi:[1,0,1]
	v_lshlrev_b32_e32 v26, 16, v29
	v_and_b32_e32 v27, 0xffff0000, v29
	v_pk_add_f32 v[26:27], v[26:27], v[36:37] neg_lo:[0,1] neg_hi:[0,1]
	s_nop 0
	v_pk_mul_f32 v[26:27], v[38:39], v[26:27]
	s_nop 0
	v_pk_fma_f32 v[26:27], v[32:33], v[26:27], v[48:49]
	s_nop 0
	v_pk_fma_f32 v[20:21], v[26:27], s[86:87], v[20:21] op_sel_hi:[1,0,1]
	s_cbranch_vccnz .LBB0_2044
	global_store_dwordx4 v[40:41], v[22:25], off offset:512
	global_store_dwordx4 v[40:41], v[18:21], off offset:528
	s_cbranch_execnz .LBB0_2023

; DI u32x4 pack8(const float (&v)[8]) { u32x4 w; w.x = pk2(v[0], v[1]); w.y = pk2(v[2], v[3]); w.z = pk2(v[4], v[5]); w.w = pk2(v[6], v[7]); return w; }
;     DI void operator()(const f32x4 (&acc)[2][2][4][2], const pg8::Unit& u, int wr, int wc, int fr, int fq) const {
;     ...
;                 for (int bj = 0; bj < 2; ++bj) { float p[8]; unpack8(*(const u32x4*)(XBin + off + bj * 128), p);
;                     const f32x4 g0 = *(const f32x4*)(g + col0 + bj * 128), g1 = *(const f32x4*)(g + col0 + bj * 128 + 4), b0 = *(const f32x4*)(b + col0 + bj * 128), b1 = *(const f32x4*)(b + col0 + bj * 128 + 4);
;                     float o[8];
; #pragma unroll
;                     for (int k = 0; k < 8; ++k) { const float gg = k < 4 ? g0[k & 3] : g1[k & 3], bb = k < 4 ? b0[k & 3] : b1[k & 3]; const float x1 = (p[k] - mu) * rstd * gg + bb; o[k] = x1 * ALPHA + acc[ai][bj][m][k >> 2][k & 3]; }
;                     if (out32) { *(f32x4*)(out32 + off + bj * 128) = (f32x4){o[0], o[1], o[2], o[3]}; *(f32x4*)(out32 + off + bj * 128 + 4) = (f32x4){o[4], o[5], o[6], o[7]}; }
;                     else *(u32x4*)(XBout + off + bj * 128) = pack8(o); }
.LBB0_2026:
	s_nop 1
	v_mov_b32_e32 v10, v174
	v_mov_b32_e32 v11, v175
	v_mov_b32_e32 v12, v176
	v_mov_b32_e32 v13, v177
	s_nop 0
	s_nop 1
	v_mov_b32_e32 v14, v242
	v_mov_b32_e32 v15, v243
	v_mov_b32_e32 v16, v244
	v_mov_b32_e32 v17, v245
	v_mov_b32_e32 v26, v246
	v_mov_b32_e32 v27, v247
	v_mov_b32_e32 v28, v248
	v_mov_b32_e32 v29, v249
	v_mov_b32_e32 v30, v250
	v_mov_b32_e32 v31, v251
	v_mov_b32_e32 v32, v252
	v_mov_b32_e32 v33, v253
	v_mov_b32_e32 v34, v240
	v_mov_b32_e32 v35, v241
	v_mov_b32_e32 v36, v186
	v_mov_b32_e32 v37, v187
	v_mov_b32_e32 v21, v20
	v_mov_b32_e32 v23, v22
	s_and_b64 vcc, exec, s[18:19]
	s_nop 0
	v_lshlrev_b32_e32 v38, 16, v10
	v_and_b32_e32 v39, 0xffff0000, v10
	v_lshlrev_b32_e32 v10, 16, v11
	v_and_b32_e32 v11, 0xffff0000, v11
	v_pk_add_f32 v[10:11], v[10:11], v[20:21] neg_lo:[0,1] neg_hi:[0,1]
	v_pk_add_f32 v[38:39], v[38:39], v[20:21] neg_lo:[0,1] neg_hi:[0,1]
	v_pk_mul_f32 v[10:11], v[22:23], v[10:11]
	v_pk_mul_f32 v[38:39], v[22:23], v[38:39]
	s_nop 0
	v_pk_fma_f32 v[10:11], v[28:29], v[10:11], v[36:37]
	v_pk_fma_f32 v[26:27], v[26:27], v[38:39], v[34:35]
	v_pk_fma_f32 v[8:9], v[10:11], s[86:87], v[8:9] op_sel_hi:[1,0,1]
	v_lshlrev_b32_e32 v10, 16, v12
	v_and_b32_e32 v11, 0xffff0000, v12
	v_pk_add_f32 v[10:11], v[10:11], v[20:21] neg_lo:[0,1] neg_hi:[0,1]
	v_pk_fma_f32 v[6:7], v[26:27], s[86:87], v[6:7] op_sel_hi:[1,0,1]
	v_pk_mul_f32 v[10:11], v[22:23], v[10:11]
	s_nop 0
	v_pk_fma_f32 v[10:11], v[14:15], v[10:11], v[30:31]
	s_nop 0
	v_pk_fma_f32 v[2:3], v[10:11], s[86:87], v[2:3] op_sel_hi:[1,0,1]
	v_lshlrev_b32_e32 v10, 16, v13
	v_and_b32_e32 v11, 0xffff0000, v13
	v_pk_add_f32 v[10:11], v[10:11], v[20:21] neg_lo:[0,1] neg_hi:[0,1]
	s_nop 0
	v_pk_mul_f32 v[10:11], v[22:23], v[10:11]
	s_nop 0
	v_pk_fma_f32 v[10:11], v[16:17], v[10:11], v[32:33]
	s_nop 0
	v_pk_fma_f32 v[4:5], v[10:11], s[86:87], v[4:5] op_sel_hi:[1,0,1]
	s_cbranch_vccnz .LBB0_2046
	global_store_dwordx4 v[24:25], v[6:9], off offset:512
	global_store_dwordx4 v[24:25], v[2:5], off offset:528
	s_cbranch_execnz .LBB0_2029
